# on top of v135: NA next-step rows staged to LDS between the two slots; DA K(i+2) loads spread over slot 3 gaps; tile-0 staging stores spread over its last PV block
# speedup vs baseline: 1.0153x; 1.0003x over previous
; __device__ void na_super(char* lds, const Params& p, int layer, int su) {
;     ...
;         for (int slot = 0; slot < 2; ++slot) {
;             const int kr = klo + 2 * st + slot;
;             if (kr >= rsw && kr <= rsw + 7) {
;                 const char* cK = cur + slot * 64 * NA_P + krow_off;
;                 const char* cV = cur + NA_KBYTES + slot * 64 * NA_P + vrow_off;
;                 const float* rpr = rph + (kr - rq + 7) * 31;
;                 float v[4][8];
; #pragma unroll
;                 for (int n = 0; n < 4; ++n) {
;                     const int kcstart = n == 0 ? 0 : (n == 1 ? 8 : (n == 2 ? 24 : 32));
;                     const int qcol = 16 * n + fr;
;                     const float* bp = rpr + (kcstart + 8 * fq - qcol + 15);
; #pragma unroll
;                     for (int e = 0; e < 8; ++e) v[n][e] = bp[e];
;                 }
; #pragma unroll
;                 for (int np = 0; np < 2; ++np) {
;                     bf16x8 kfr[2][4];
; #pragma unroll
;                     for (int q = 0; q < 2; ++q) {
;                         const int n = 2 * np + q;
;                         const int kcstart = n == 0 ? 0 : (n == 1 ? 8 : (n == 2 ? 24 : 32));
; #pragma unroll
;                         for (int T = 0; T < 2; ++T) { kfr[q][2 * T] = *(const bf16x8*)(cK + (kcstart + T * 4) * NA_P); kfr[q][2 * T + 1] = *(const bf16x8*)(cK + (kcstart + T * 4) * NA_P + 64); }
;                     }
; #pragma unroll
;                     for (int q = 0; q < 2; ++q) {
;                         const int n = 2 * np + q;
;                         const int kcstart = n == 0 ? 0 : (n == 1 ? 8 : (n == 2 ? 24 : 32));
;                         const int qcol = 16 * n + fr;
;                         const int qcstart = min(max(qcol - 8, 0), 48);
; #pragma unroll
;                         for (int T = 0; T < 2; ++T) {
;                             f32x4 s = (f32x4){mrow[n], mrow[n], mrow[n], mrow[n]};
;                             s = __builtin_amdgcn_mfma_f32_16x16x32_bf16(kfr[q][2 * T], qf[n][0], s, 0, 0, 0);
;                             s = __builtin_amdgcn_mfma_f32_16x16x32_bf16(kfr[q][2 * T + 1], qf[n][1], s, 0, 0, 0);
; #pragma unroll
;                             for (int e = 0; e < 4; ++e) {
;                                 const int kcol = kcstart + 8 * fq + e + 4 * T;
.LBB0_457:
	s_xor_b64 s[78:79], s[2:3], -1
	s_mov_b32 s76, 1
	s_mov_b64 s[2:3], 0
	s_and_b64 vcc, exec, s[78:79]
	s_cbranch_vccnz .LBB0_460
	s_and_b64 vcc, exec, s[0:1]
	s_cbranch_vccz .Lna_nw
	s_bitcmp1_b32 s70, 0
	s_cselect_b32 s77, 0x9000, 0
	v_add_u32_e32 v251, s77, v129
	s_waitcnt vmcnt(3)
	ds_write_b128 v251, v[100:103]
	s_waitcnt vmcnt(2)
	ds_write_b128 v251, v[104:107] offset:9216
	s_waitcnt vmcnt(1)
	ds_write_b128 v251, v[108:111] offset:18432
	s_waitcnt vmcnt(0)
	ds_write_b128 v251, v[112:115] offset:27648
.Lna_nw:
.LBB0_458:
	s_mul_i32 s77, s76, s101
	s_add_i32 s77, s77, s72
	s_cmp_lt_u32 s77, s92
	s_cselect_b64 s[78:79], -1, 0
	s_cmp_gt_u32 s77, s97
	s_cselect_b64 s[80:81], -1, 0
	s_or_b64 s[78:79], s[78:79], s[80:81]
	s_and_b64 vcc, exec, s[78:79]
	s_cbranch_vccnz .LBB0_457
	s_sub_i32 s77, s77, s74
	s_mulk_i32 s77, 0x7c
	s_mulk_i32 s76, 0x2400
	v_add_u32_e32 v154, s77, v146
	v_add_u32_e32 v149, s76, v147
	ds_read2_b32 v[150:151], v154 offset0:232 offset1:233
	ds_read2_b32 v[156:157], v154 offset0:234 offset1:235
	ds_read2_b32 v[158:159], v154 offset0:236 offset1:237
	ds_read2_b32 v[160:161], v154 offset0:238 offset1:239
	ds_read_b128 v[164:167], v149
	ds_read2_b32 v[162:163], v154 offset0:224 offset1:225
	ds_read2_b32 v[196:197], v154 offset0:226 offset1:227
	ds_read2_b32 v[198:199], v154 offset0:228 offset1:229
	ds_read2_b32 v[200:201], v154 offset0:230 offset1:231
	ds_read_b128 v[168:171], v149 offset:64
	ds_read2_b32 v[202:203], v154 offset0:216 offset1:217
	ds_read2_b32 v[204:205], v154 offset0:218 offset1:219
	ds_read2_b32 v[206:207], v154 offset0:220 offset1:221
	ds_read2_b32 v[208:209], v154 offset0:222 offset1:223
	ds_read_b128 v[172:175], v149 offset:576
	ds_read_b128 v[176:179], v149 offset:640
	s_waitcnt lgkmcnt(11)
	v_mfma_f32_16x16x32_bf16 v[164:167], v[164:167], v[56:59], v[84:87]
	ds_read_b128 v[180:183], v149 offset:1152
	ds_read_b128 v[184:187], v149 offset:1216
	ds_read_b128 v[188:191], v149 offset:1728
	ds_read_b128 v[192:195], v149 offset:1792
	v_add_u32_e32 v226, s76, v148
	s_waitcnt lgkmcnt(10)
	v_mfma_f32_16x16x32_bf16 v[164:167], v[168:171], v[60:63], v[164:167]
	s_waitcnt lgkmcnt(5)
	v_mfma_f32_16x16x32_bf16 v[168:171], v[172:175], v[56:59], v[84:87]
	s_nop 5
	v_fmac_f32_e32 v151, 0x3e38aa3b, v165
	v_fmamk_f32 v150, v164, 0x3e38aa3b, v150
	v_cndmask_b32_e64 v154, v243, v151, s[6:7]
	v_fmamk_f32 v151, v166, 0x3e38aa3b, v156
	v_fmac_f32_e32 v157, 0x3e38aa3b, v167
	s_waitcnt lgkmcnt(4)
	v_mfma_f32_16x16x32_bf16 v[164:167], v[176:179], v[60:63], v[168:171]
	v_cndmask_b32_e64 v156, v243, v151, s[8:9]
	v_cndmask_b32_e64 v150, v243, v150, s[4:5]
	v_cndmask_b32_e64 v210, v243, v157, s[10:11]
	s_waitcnt lgkmcnt(3)
	v_mfma_f32_16x16x32_bf16 v[168:171], v[180:183], v[64:67], v[116:119]
	v_exp_f32_e32 v157, v154
	s_nop 1
	v_fmamk_f32 v151, v164, 0x3e38aa3b, v158
	v_cndmask_b32_e64 v158, v243, v151, s[12:13]
	v_fmac_f32_e32 v159, 0x3e38aa3b, v165
	v_fmamk_f32 v151, v166, 0x3e38aa3b, v160
	v_fmac_f32_e32 v161, 0x3e38aa3b, v167
	s_waitcnt lgkmcnt(2)
	v_mfma_f32_16x16x32_bf16 v[164:167], v[184:187], v[68:71], v[168:171]
	v_cndmask_b32_e64 v160, v243, v151, s[16:17]
	v_cndmask_b32_e64 v211, v243, v159, s[14:15]
	v_cndmask_b32_e64 v212, v243, v161, s[18:19]
	s_waitcnt lgkmcnt(1)
	v_mfma_f32_16x16x32_bf16 v[168:171], v[188:191], v[64:67], v[116:119]
	v_exp_f32_e32 v159, v156
	s_nop 1
	v_fmamk_f32 v151, v164, 0x3e38aa3b, v162
	v_cndmask_b32_e64 v213, v243, v151, s[20:21]
	v_fmamk_f32 v151, v165, 0x3e38aa3b, v163
	v_cndmask_b32_e64 v214, v243, v151, s[22:23]
	v_fmamk_f32 v151, v166, 0x3e38aa3b, v196
	v_cndmask_b32_e64 v215, v243, v151, s[24:25]
	v_fmamk_f32 v151, v167, 0x3e38aa3b, v197
	s_waitcnt lgkmcnt(0)
	v_mfma_f32_16x16x32_bf16 v[164:167], v[192:195], v[68:71], v[168:171]
	v_cndmask_b32_e64 v216, v243, v151, s[26:27]
	v_exp_f32_e32 v161, v210
	v_exp_f32_e32 v156, v214
	ds_read_b128 v[168:171], v149 offset:3456
	s_nop 3
	v_fmamk_f32 v151, v164, 0x3e38aa3b, v198
	v_cndmask_b32_e64 v217, v243, v151, s[28:29]
	v_fmamk_f32 v151, v165, 0x3e38aa3b, v199
	v_cndmask_b32_e64 v218, v243, v151, s[30:31]
	v_fmamk_f32 v151, v166, 0x3e38aa3b, v200
	v_cndmask_b32_e64 v219, v243, v151, s[34:35]
	v_fmamk_f32 v151, v167, 0x3e38aa3b, v201
	ds_read_b128 v[164:167], v149 offset:3520
	ds_read_b128 v[172:175], v149 offset:4032
	ds_read_b128 v[176:179], v149 offset:4096
	s_waitcnt lgkmcnt(3)
	v_mfma_f32_16x16x32_bf16 v[168:171], v[168:171], v[76:79], v[120:123]
	ds_read_b128 v[180:183], v149 offset:4608
	ds_read_b128 v[184:187], v149 offset:4672
	ds_read_b128 v[188:191], v149 offset:5184
	ds_read_b128 v[192:195], v149 offset:5248
	v_cndmask_b32_e64 v220, v243, v151, s[36:37]
	s_waitcnt lgkmcnt(6)
	v_mfma_f32_16x16x32_bf16 v[164:167], v[164:167], v[80:83], v[168:171]
	s_waitcnt lgkmcnt(5)
	v_mfma_f32_16x16x32_bf16 v[168:171], v[172:175], v[76:79], v[120:123]
	s_nop 5
	v_fmamk_f32 v149, v164, 0x3e38aa3b, v162
	v_fmac_f32_e32 v163, 0x3e38aa3b, v165
	v_fmamk_f32 v151, v166, 0x3e38aa3b, v196
	v_fmac_f32_e32 v197, 0x3e38aa3b, v167
	s_waitcnt lgkmcnt(4)
	v_mfma_f32_16x16x32_bf16 v[164:167], v[176:179], v[80:83], v[168:171]
	v_cndmask_b32_e64 v222, v243, v151, s[42:43]
	ds_read_b128 v[176:179], v226 offset:20736
	v_cndmask_b32_e64 v221, v243, v163, s[40:41]
	s_waitcnt lgkmcnt(4)
	v_mfma_f32_16x16x32_bf16 v[168:171], v[180:183], v[92:95], v[124:127]
	v_cndmask_b32_e64 v223, v243, v197, s[44:45]
	s_nop 1
	v_fmamk_f32 v151, v164, 0x3e38aa3b, v198
	v_cndmask_b32_e64 v198, v243, v151, s[46:47]
	v_fmac_f32_e32 v199, 0x3e38aa3b, v165
	v_fmamk_f32 v151, v166, 0x3e38aa3b, v200
	v_fmac_f32_e32 v201, 0x3e38aa3b, v167
	s_waitcnt lgkmcnt(3)
; __device__ __forceinline__ float fast_exp2(float x) { return __builtin_amdgcn_exp2f(x); }
; __device__ void na_super(char* lds, const Params& p, int layer, int su) {
;     ...
; #pragma unroll
;                 for (int n = 0; n < 4; ++n) {
;                     const int kcstart = n == 0 ? 0 : (n == 1 ? 8 : (n == 2 ? 24 : 32));
;                     float ps = 0.f;
; #pragma unroll
;                     for (int e = 0; e < 8; ++e) { v[n][e] = fast_exp2(v[n][e]); ps += v[n][e]; }
;                     lrow[n] += ps;
;                     u32x4 w;
;                     w.x = cvt_pk_bf16(v[n][0], v[n][1]); w.y = cvt_pk_bf16(v[n][2], v[n][3]); w.z = cvt_pk_bf16(v[n][4], v[n][5]); w.w = cvt_pk_bf16(v[n][6], v[n][7]);
;                     const bf16x8 pb = __builtin_bit_cast(bf16x8, w);
; #pragma unroll
;                     for (int dt = 0; dt < 4; ++dt) {
;                         const bf16x8 vf = *(const bf16x8*)(cV + dt * 16 * NA_P + kcstart * 2);
;                         O[n][dt] = __builtin_amdgcn_mfma_f32_16x16x32_bf16(vf, pb, O[n][dt], 0, 0, 0);
;                     }
;                 }
;             }
;         }
;         if (st + 1 < nsteps) {
;             *(u32x4*)(nxt + lw) = rk[0]; *(u32x4*)(nxt + lw + 64 * NA_P) = rk[1];
;             *(u32x4*)(nxt + NA_KBYTES + lw) = rv[0]; *(u32x4*)(nxt + NA_KBYTES + lw + 64 * NA_P) = rv[1];
;         }
;         __syncthreads();
	v_mfma_f32_16x16x32_bf16 v[164:167], v[184:187], v[96:99], v[168:171]
	v_cndmask_b32_e64 v200, v243, v151, s[50:51]
	v_exp_f32_e32 v163, v158
	v_exp_f32_e32 v197, v212
	s_waitcnt lgkmcnt(2)
	v_mfma_f32_16x16x32_bf16 v[168:171], v[188:191], v[92:95], v[124:127]
	v_cvt_pk_bf16_f32 v173, v159, v161
	s_nop 1
	v_fmamk_f32 v151, v164, 0x3e38aa3b, v202
	v_cndmask_b32_e64 v202, v243, v151, s[54:55]
	v_fmac_f32_e32 v203, 0x3e38aa3b, v165
	v_fmamk_f32 v151, v166, 0x3e38aa3b, v204
	v_fmac_f32_e32 v205, 0x3e38aa3b, v167
	s_waitcnt lgkmcnt(1)
	v_mfma_f32_16x16x32_bf16 v[164:167], v[192:195], v[96:99], v[168:171]
	v_cndmask_b32_e64 v204, v243, v151, s[58:59]
	v_exp_f32_e32 v151, v150
	v_exp_f32_e32 v193, v211
	ds_read_b128 v[168:171], v226 offset:18432
	v_exp_f32_e32 v195, v160
	ds_read_b128 v[180:183], v226 offset:18448
	ds_read_b128 v[184:187], v226 offset:23040
	v_cvt_pk_bf16_f32 v172, v151, v157
	v_cvt_pk_bf16_f32 v174, v163, v193
	v_cvt_pk_bf16_f32 v175, v195, v197
	v_fmamk_f32 v150, v164, 0x3e38aa3b, v206
	v_cndmask_b32_e64 v154, v243, v205, s[60:61]
	s_waitcnt lgkmcnt(2)
	v_mfma_f32_16x16x32_bf16 v[88:91], v[168:171], v[172:175], v[88:91]
	ds_read_b128 v[168:171], v226 offset:25344
	ds_read_b128 v[188:191], v226 offset:20752
	v_cndmask_b32_e64 v205, v243, v150, s[62:63]
	v_exp_f32_e32 v150, v213
	v_mfma_f32_16x16x32_bf16 v[72:75], v[176:179], v[172:175], v[72:75]
	ds_read_b128 v[176:179], v226 offset:23056
	v_fmac_f32_e32 v207, 0x3e38aa3b, v165
	v_exp_f32_e32 v158, v215
	s_waitcnt lgkmcnt(3)
	v_mfma_f32_16x16x32_bf16 v[52:55], v[184:187], v[172:175], v[52:55]
	ds_read_b128 v[184:187], v226 offset:25360
	v_exp_f32_e32 v160, v216
	v_exp_f32_e32 v162, v217
	v_exp_f32_e32 v192, v218
	v_exp_f32_e32 v194, v219
	v_exp_f32_e32 v196, v220
	v_fmamk_f32 v164, v166, 0x3e38aa3b, v208
	v_cndmask_b32_e64 v206, v243, v207, s[64:65]
	s_waitcnt lgkmcnt(3)
	v_mfma_f32_16x16x32_bf16 v[48:51], v[168:171], v[172:175], v[48:51]
	v_cndmask_b32_e64 v207, v243, v164, s[66:67]
	v_fmac_f32_e32 v209, 0x3e38aa3b, v167
	ds_read_b128 v[164:167], v226 offset:18480
	ds_read_b128 v[172:175], v226 offset:20784
	v_cvt_pk_bf16_f32 v168, v150, v156
	v_pk_add_f32 v[150:151], v[150:151], 0 op_sel_hi:[1,0]
	v_cndmask_b32_e64 v149, v243, v149, s[38:39]
	v_pk_add_f32 v[150:151], v[156:157], v[150:151]
	v_cndmask_b32_e64 v199, v243, v199, s[48:49]
	v_cndmask_b32_e64 v224, v243, v201, s[52:53]
	v_cvt_pk_bf16_f32 v169, v158, v160
	v_cvt_pk_bf16_f32 v170, v162, v192
	v_cvt_pk_bf16_f32 v171, v194, v196
	v_pk_add_f32 v[150:151], v[158:159], v[150:151]
	v_cndmask_b32_e64 v225, v243, v203, s[56:57]
	s_waitcnt lgkmcnt(4)
	v_mfma_f32_16x16x32_bf16 v[40:43], v[188:191], v[168:171], v[40:43]
	v_add_f32_e64 v150, v160, v150
	v_add_f32_e64 v151, v161, v151
	v_exp_f32_e32 v157, v149
	v_exp_f32_e32 v159, v221
	v_exp_f32_e32 v161, v222
	v_exp_f32_e32 v189, v223
	v_exp_f32_e32 v191, v198
	v_exp_f32_e32 v199, v199
	v_exp_f32_e32 v201, v200
	v_exp_f32_e32 v203, v224
	v_mfma_f32_16x16x32_bf16 v[44:47], v[180:183], v[168:171], v[44:47]
	v_add_f32_e64 v150, v162, v150
	v_add_f32_e64 v151, v163, v151
	v_exp_f32_e32 v156, v202
	v_pk_add_f32 v[150:151], v[192:193], v[150:151]
	s_waitcnt lgkmcnt(3)
	v_mfma_f32_16x16x32_bf16 v[36:39], v[176:179], v[168:171], v[36:39]
	ds_read_b128 v[176:179], v226 offset:23088
	ds_read_b128 v[180:183], v226 offset:18496
	v_exp_f32_e32 v158, v225
	v_pk_add_f32 v[150:151], v[194:195], v[150:151]
	s_waitcnt lgkmcnt(4)
	v_mfma_f32_16x16x32_bf16 v[32:35], v[184:187], v[168:171], v[32:35]
	v_cvt_pk_bf16_f32 v168, v157, v159
	v_cvt_pk_bf16_f32 v169, v161, v189
	v_cvt_pk_bf16_f32 v170, v191, v199
	v_cvt_pk_bf16_f32 v171, v201, v203
	v_exp_f32_e32 v160, v204
	v_cndmask_b32_e64 v208, v243, v209, s[68:69]
	s_waitcnt lgkmcnt(3)
	v_mfma_f32_16x16x32_bf16 v[28:31], v[164:167], v[168:171], v[28:31]
	ds_read_b128 v[164:167], v226 offset:25392
	ds_read_b128 v[184:187], v226 offset:20800
	v_pk_add_f32 v[150:151], v[196:197], v[150:151]
	v_exp_f32_e32 v188, v154
	s_waitcnt lgkmcnt(4)
	v_mfma_f32_16x16x32_bf16 v[24:27], v[172:175], v[168:171], v[24:27]
	ds_read_b128 v[172:175], v226 offset:23104
	v_pk_add_f32 v[136:137], v[136:137], v[150:151]
	v_exp_f32_e32 v190, v205
	s_waitcnt lgkmcnt(4)
	v_mfma_f32_16x16x32_bf16 v[20:23], v[176:179], v[168:171], v[20:23]
	ds_read_b128 v[176:179], v226 offset:25408
	v_exp_f32_e32 v198, v206
	v_exp_f32_e32 v200, v207
	v_exp_f32_e32 v202, v208
	v_pk_add_f32 v[150:151], v[156:157], 0 op_sel_hi:[1,0]
	s_waitcnt lgkmcnt(3)
	v_mfma_f32_16x16x32_bf16 v[16:19], v[164:167], v[168:171], v[16:19]
	v_add_f32_e64 v150, v158, v150
	v_add_f32_e64 v151, v159, v151
	v_cvt_pk_bf16_f32 v164, v156, v158
	v_pk_add_f32 v[150:151], v[160:161], v[150:151]
	v_cvt_pk_bf16_f32 v165, v160, v188
	v_pk_add_f32 v[150:151], v[188:189], v[150:151]
	v_cvt_pk_bf16_f32 v166, v190, v198
	v_cvt_pk_bf16_f32 v167, v200, v202
	v_pk_add_f32 v[150:151], v[190:191], v[150:151]
	s_nop 0
	v_mfma_f32_16x16x32_bf16 v[12:15], v[180:183], v[164:167], v[12:15]
	v_add_f32_e64 v150, v198, v150
	v_add_f32_e64 v151, v199, v151
	v_pk_add_f32 v[150:151], v[200:201], v[150:151]
	s_waitcnt lgkmcnt(2)
	v_mfma_f32_16x16x32_bf16 v[8:11], v[184:187], v[164:167], v[8:11]
	v_add_f32_e64 v150, v202, v150
	v_add_f32_e64 v151, v203, v151
	v_pk_add_f32 v[134:135], v[134:135], v[150:151]
	s_waitcnt lgkmcnt(1)
	v_mfma_f32_16x16x32_bf16 v[4:7], v[172:175], v[164:167], v[4:7]
	s_waitcnt lgkmcnt(0)
	v_mfma_f32_16x16x32_bf16 v[0:3], v[176:179], v[164:167], v[0:3]
	s_branch .LBB0_457
.LBB0_460:
.LBB0_462:
	s_cmp_eq_u32 s70, s96
	s_waitcnt lgkmcnt(0)
	s_barrier
	s_cbranch_scc1 .LBB0_464
	s_mov_b32 s2, s70
	s_branch .LBB0_454

; __device__ __forceinline__ float bflo(unsigned w) { return __uint_as_float(w << 16); }
; __device__ __forceinline__ float bfhi(unsigned w) { return __uint_as_float(w & 0xffff0000u); }
; __device__ void da_unit(char* lds, const Params& p, int layer, int unit) {
;     ...
;     for (int t = 0; t < 4; ++t) {
;         const u32x4 w = *(const u32x4*)(p.z + ZS_QD + ((size_t)(bh * 2048 + q0 + r)) * 128 + c * 64 + t * 16 + h2 * 8);
;         u32x4 o;
;         o.x = cvt_pk_bf16(bflo(w.x) * qscale, bfhi(w.x) * qscale); o.y = cvt_pk_bf16(bflo(w.y) * qscale, bfhi(w.y) * qscale);
;         o.z = cvt_pk_bf16(bflo(w.z) * qscale, bfhi(w.z) * qscale); o.w = cvt_pk_bf16(bflo(w.w) * qscale, bfhi(w.w) * qscale);
;         qf[t] = __builtin_bit_cast(bf16x8, o);
;     }
;     ...
;     const int pr = (r & 0x13) | ((r & 4) << 1) | ((r & 8) >> 1);
;     if (wid >= 4) __builtin_amdgcn_s_setprio(1);
;     {
;         const int it = 0; const int kt = qb;
;         const char* cK = lds + (it & 1) * DA_STAGE;
;         const char* cV = cK + DA_KBYTES;
;         char* nK = lds + ((it + 1) & 1) * DA_STAGE;
;         if (it + 1 < NT) {
;             const int tn = tile_of(it + 1);
; #pragma unroll
;             for (int j = 0; j < 4; ++j) { rk[j] = *(const u32x4*)(Kg + (size_t)tn * 16384 + j * 4096); rv[j] = *(const u32x4*)(Vg + (size_t)tn * 16384 + j * 4096); }
;         }
; #pragma unroll
;         for (int kb = 0; kb < 4; ++kb) {
;             const int k0 = kt * 128 + kb * 32;
;             f32x16 s; const float A = 0.f;
;             const float kq = (float)k0 + qrel;
; #pragma unroll
;             for (int e = 0; e < 16; ++e) s[e] = 0.f;
; #pragma unroll
;             for (int t = 0; t < 4; ++t) {
;                 const bf16x8 kf = *(const bf16x8*)(cK + (kb * 32 + pr) * DA_KP + c * 128 + t * 32 + h2 * 16);
;                 s = __builtin_amdgcn_mfma_f32_32x32x16_bf16(kf, qf[t], s, 0, 0, 0);
;             }
; #pragma unroll
;             for (int e = 0; e < 16; ++e) s[e] = fmaf(fabsf(kq + (float)(16 * (e >> 3) + (e & 7))), -slope2, s[e]);
.LBB0_478:
	v_ldexp_f32 v19, 1.0, s1
	s_mov_b32 s10, 0x3e38aa3b
	v_mul_f32_e32 v65, 0x3fb8aa3b, v19
	s_add_i32 s0, s14, 1
	s_cmp_lg_u32 s14, 15
	s_cselect_b32 s0, s0, 14
	s_lshl_b32 s18, s0, 15
	s_mov_b32 s19, 0
	v_lshl_add_u64 v[156:157], v[148:149], 0, s[18:19]
	global_load_dwordx4 v[130:133], v[156:157], off
	s_add_u32 s18, s18, 0x2000
	v_lshl_add_u64 v[156:157], v[148:149], 0, s[18:19]
	global_load_dwordx4 v[134:137], v[156:157], off
	s_add_u32 s18, s18, 0x2000
	v_lshl_add_u64 v[156:157], v[148:149], 0, s[18:19]
	global_load_dwordx4 v[138:141], v[156:157], off
	s_add_u32 s18, s18, 0x2000
	v_lshl_add_u64 v[156:157], v[148:149], 0, s[18:19]
	global_load_dwordx4 v[142:145], v[156:157], off
	s_lshl_b32 s18, s0, 15
	s_mov_b32 s19, 0
	v_lshl_add_u64 v[156:157], v[150:151], 0, s[18:19]
	global_load_dwordx4 v[66:69], v[156:157], off
	s_add_u32 s18, s18, 0x2000
	v_lshl_add_u64 v[156:157], v[150:151], 0, s[18:19]
	global_load_dwordx4 v[70:73], v[156:157], off
	s_add_u32 s18, s18, 0x2000
	v_lshl_add_u64 v[156:157], v[150:151], 0, s[18:19]
	global_load_dwordx4 v[74:77], v[156:157], off
	s_add_u32 s18, s18, 0x2000
	v_lshl_add_u64 v[156:157], v[150:151], 0, s[18:19]
	global_load_dwordx4 v[78:81], v[156:157], off
	v_lshlrev_b32_e32 v242, 1, v187
	v_and_b32_e32 v242, 8, v242
	v_lshrrev_b32_e32 v253, 1, v187
	v_and_b32_e32 v253, 4, v253
	v_and_b32_e32 v241, 19, v187
	v_or3_b32 v241, v242, v241, v253
	v_mul_u32_u24_e32 v186, 0x110, v241
	v_mul_u32_u24_e32 v154, 0x90, v147
	v_add_u32_e32 v168, 0x3600, v154
	v_lshlrev_b32_e32 v252, 3, v188
	v_cvt_f32_ubyte0_e32 v242, v252
	v_or_b32_e32 v253, s7, v147
	v_cvt_f32_i32_e32 v253, v253
	v_sub_f32_e32 v185, v242, v253
	v_add3_u32 v234, s8, v186, v152
	s_mov_b32 s2, 0x8800
	v_add3_u32 v235, s2, v152, v154
	s_lshl_b32 s11, s14, 7
	ds_read_b128 v[210:213], v234 offset:0
	ds_read_b128 v[214:217], v234 offset:32
	ds_read_b128 v[218:221], v234 offset:64
	ds_read_b128 v[222:225], v234 offset:96
	s_waitcnt vmcnt(11)
	v_lshlrev_b32_e32 v242, 16, v8
	v_and_b32_e32 v253, 0xffff0000, v8
	v_mul_f32_e32 v242, s10, v242
	v_mul_f32_e32 v253, s10, v253
	v_cvt_pk_bf16_f32 v114, v242, v253
	v_lshlrev_b32_e32 v241, 16, v9
	v_and_b32_e32 v236, 0xffff0000, v9
	v_mul_f32_e32 v241, s10, v241
	v_mul_f32_e32 v236, s10, v236
	v_cvt_pk_bf16_f32 v115, v241, v236
	v_lshlrev_b32_e32 v242, 16, v10
	v_and_b32_e32 v253, 0xffff0000, v10
	v_mul_f32_e32 v242, s10, v242
	v_mul_f32_e32 v253, s10, v253
	v_cvt_pk_bf16_f32 v116, v242, v253
	v_lshlrev_b32_e32 v241, 16, v11
	v_and_b32_e32 v236, 0xffff0000, v11
	v_mul_f32_e32 v241, s10, v241
	v_mul_f32_e32 v236, s10, v236
	v_cvt_pk_bf16_f32 v117, v241, v236
	s_waitcnt vmcnt(10)
	v_lshlrev_b32_e32 v242, 16, v4
	v_and_b32_e32 v253, 0xffff0000, v4
	v_mul_f32_e32 v242, s10, v242
	v_mul_f32_e32 v253, s10, v253
	v_cvt_pk_bf16_f32 v118, v242, v253
	v_lshlrev_b32_e32 v241, 16, v5
	v_and_b32_e32 v236, 0xffff0000, v5
	v_mul_f32_e32 v241, s10, v241
	v_mul_f32_e32 v236, s10, v236
	v_cvt_pk_bf16_f32 v119, v241, v236
	v_lshlrev_b32_e32 v242, 16, v6
	v_and_b32_e32 v253, 0xffff0000, v6
	v_mul_f32_e32 v242, s10, v242
	v_mul_f32_e32 v253, s10, v253
	v_cvt_pk_bf16_f32 v120, v242, v253
	v_lshlrev_b32_e32 v241, 16, v7
	v_and_b32_e32 v236, 0xffff0000, v7
	v_mul_f32_e32 v241, s10, v241
	v_mul_f32_e32 v236, s10, v236
	v_cvt_pk_bf16_f32 v121, v241, v236
	s_waitcnt vmcnt(9)
	v_lshlrev_b32_e32 v242, 16, v0
	v_and_b32_e32 v253, 0xffff0000, v0
	v_mul_f32_e32 v242, s10, v242
	v_mul_f32_e32 v253, s10, v253
	v_cvt_pk_bf16_f32 v122, v242, v253
	v_lshlrev_b32_e32 v241, 16, v1
	v_and_b32_e32 v236, 0xffff0000, v1
	v_mul_f32_e32 v241, s10, v241
	v_mul_f32_e32 v236, s10, v236
	v_cvt_pk_bf16_f32 v123, v241, v236
	v_lshlrev_b32_e32 v242, 16, v2
	v_and_b32_e32 v253, 0xffff0000, v2
	v_mul_f32_e32 v242, s10, v242
	v_mul_f32_e32 v253, s10, v253
	v_cvt_pk_bf16_f32 v124, v242, v253
	v_lshlrev_b32_e32 v241, 16, v3
	v_and_b32_e32 v236, 0xffff0000, v3
	v_mul_f32_e32 v241, s10, v241
	v_mul_f32_e32 v236, s10, v236
	v_cvt_pk_bf16_f32 v125, v241, v236
	s_waitcnt vmcnt(8)
	v_lshlrev_b32_e32 v242, 16, v14
	v_and_b32_e32 v253, 0xffff0000, v14
	v_mul_f32_e32 v242, s10, v242
	v_mul_f32_e32 v253, s10, v253
	v_cvt_pk_bf16_f32 v126, v242, v253
	v_lshlrev_b32_e32 v241, 16, v15
	v_and_b32_e32 v236, 0xffff0000, v15
	v_mul_f32_e32 v241, s10, v241
	v_mul_f32_e32 v236, s10, v236
	v_cvt_pk_bf16_f32 v127, v241, v236
	v_lshlrev_b32_e32 v242, 16, v16
	v_and_b32_e32 v253, 0xffff0000, v16
	v_mul_f32_e32 v242, s10, v242
	v_mul_f32_e32 v253, s10, v253
	v_cvt_pk_bf16_f32 v128, v242, v253
	v_lshlrev_b32_e32 v241, 16, v17
	v_and_b32_e32 v236, 0xffff0000, v17
	v_mul_f32_e32 v241, s10, v241
	v_mul_f32_e32 v236, s10, v236
	v_cvt_pk_bf16_f32 v129, v241, v236
	s_mov_b32 s2, s11
	v_cvt_f32_u32_e32 v239, s2
	v_add_f32_e32 v239, v185, v239
	v_mul_f32_e64 v82, |v239|, -v65
	v_add_f32_e32 v253, 1.0, v239
	v_mul_f32_e64 v83, |v253|, -v65
	v_add_f32_e32 v253, 2.0, v239
	v_mul_f32_e64 v84, |v253|, -v65
	v_add_f32_e32 v253, 0x40400000, v239
	v_mul_f32_e64 v85, |v253|, -v65
	v_add_f32_e32 v253, 4.0, v239
	v_mul_f32_e64 v86, |v253|, -v65
	v_add_f32_e32 v253, 0x40a00000, v239
	v_mul_f32_e64 v87, |v253|, -v65
	v_add_f32_e32 v253, 0x40c00000, v239
	v_mul_f32_e64 v88, |v253|, -v65
	v_add_f32_e32 v253, 0x40e00000, v239
	v_mul_f32_e64 v89, |v253|, -v65
	v_add_f32_e32 v253, 0x41800000, v239
	v_mul_f32_e64 v90, |v253|, -v65
	v_add_f32_e32 v253, 0x41880000, v239
	v_mul_f32_e64 v91, |v253|, -v65
	v_add_f32_e32 v253, 0x41900000, v239
	v_mul_f32_e64 v92, |v253|, -v65
	v_add_f32_e32 v253, 0x41980000, v239
	v_mul_f32_e64 v93, |v253|, -v65
	v_add_f32_e32 v253, 0x41a00000, v239
	v_mul_f32_e64 v94, |v253|, -v65
	v_add_f32_e32 v253, 0x41a80000, v239
	v_mul_f32_e64 v95, |v253|, -v65
	v_add_f32_e32 v253, 0x41b00000, v239
	v_mul_f32_e64 v96, |v253|, -v65
	v_add_f32_e32 v253, 0x41b80000, v239
	v_mul_f32_e64 v97, |v253|, -v65
	s_waitcnt lgkmcnt(3)
; __device__ void da_unit(char* lds, const Params& p, int layer, int unit) {
;     ...
;         for (int kb = 0; kb < 4; ++kb) {
;             const int k0 = kt * 128 + kb * 32;
;             f32x16 s; const float A = 0.f;
;             const float kq = (float)k0 + qrel;
; #pragma unroll
;             for (int e = 0; e < 16; ++e) s[e] = 0.f;
; #pragma unroll
;             for (int t = 0; t < 4; ++t) {
;                 const bf16x8 kf = *(const bf16x8*)(cK + (kb * 32 + pr) * DA_KP + c * 128 + t * 32 + h2 * 16);
;                 s = __builtin_amdgcn_mfma_f32_32x32x16_bf16(kf, qf[t], s, 0, 0, 0);
;             }
; #pragma unroll
;             for (int e = 0; e < 16; ++e) s[e] = fmaf(fabsf(kq + (float)(16 * (e >> 3) + (e & 7))), -slope2, s[e]);
	s_nop 0
	v_mfma_f32_32x32x16_bf16 v[82:97], v[210:213], v[114:117], v[82:97]
	ds_read_b128 v[210:213], v234 offset:8704
	s_add_i32 s2, s11, 32
	v_cvt_f32_u32_e32 v236, s2
	v_add_f32_e32 v236, v185, v236
	v_mul_f32_e64 v98, |v236|, -v65
	v_add_f32_e32 v253, 1.0, v236
	v_mul_f32_e64 v99, |v253|, -v65
	v_add_f32_e32 v253, 2.0, v236
	v_mul_f32_e64 v100, |v253|, -v65
	v_add_f32_e32 v253, 0x40400000, v236
	s_waitcnt lgkmcnt(3)
	v_mfma_f32_32x32x16_bf16 v[82:97], v[214:217], v[118:121], v[82:97]
	ds_read_b128 v[214:217], v234 offset:8736
	v_mul_f32_e64 v101, |v253|, -v65
	v_add_f32_e32 v253, 4.0, v236
	v_mul_f32_e64 v102, |v253|, -v65
	v_add_f32_e32 v253, 0x40a00000, v236
	v_mul_f32_e64 v103, |v253|, -v65
	v_add_f32_e32 v253, 0x40c00000, v236
	v_mul_f32_e64 v104, |v253|, -v65
	v_add_f32_e32 v253, 0x40e00000, v236
	v_mul_f32_e64 v105, |v253|, -v65
	s_waitcnt lgkmcnt(3)
	v_mfma_f32_32x32x16_bf16 v[82:97], v[218:221], v[122:125], v[82:97]
	ds_read_b128 v[218:221], v234 offset:8768
	v_add_f32_e32 v253, 0x41800000, v236
	v_mul_f32_e64 v106, |v253|, -v65
	v_add_f32_e32 v253, 0x41880000, v236
	v_mul_f32_e64 v107, |v253|, -v65
	v_add_f32_e32 v253, 0x41900000, v236
	v_mul_f32_e64 v108, |v253|, -v65
	v_add_f32_e32 v253, 0x41980000, v236
	v_mul_f32_e64 v109, |v253|, -v65
	v_add_f32_e32 v253, 0x41a00000, v236
	s_waitcnt lgkmcnt(3)
	v_mfma_f32_32x32x16_bf16 v[82:97], v[222:225], v[126:129], v[82:97]
	ds_read_b128 v[222:225], v234 offset:8800
	v_mul_f32_e64 v110, |v253|, -v65
	v_add_f32_e32 v253, 0x41a80000, v236
	v_mul_f32_e64 v111, |v253|, -v65
	v_add_f32_e32 v253, 0x41b00000, v236
	v_mul_f32_e64 v112, |v253|, -v65
	v_add_f32_e32 v253, 0x41b80000, v236
	v_mul_f32_e64 v113, |v253|, -v65
	s_waitcnt lgkmcnt(3)
	s_nop 0
	v_mfma_f32_32x32x16_bf16 v[98:113], v[210:213], v[114:117], v[98:113]
	ds_read_b128 v[210:213], v234 offset:17408
	s_add_i32 s2, s11, 64
	v_cvt_f32_u32_e32 v239, s2
	v_add_f32_e32 v239, v185, v239
	v_mul_f32_e64 v16, |v239|, -v65
	v_add_f32_e32 v253, 1.0, v239
	v_mul_f32_e64 v17, |v253|, -v65
	v_add_f32_e32 v253, 2.0, v239
	v_mul_f32_e64 v18, |v253|, -v65
	v_add_f32_e32 v253, 0x40400000, v239
	s_waitcnt lgkmcnt(3)
	v_mfma_f32_32x32x16_bf16 v[98:113], v[214:217], v[118:121], v[98:113]
	ds_read_b128 v[214:217], v234 offset:17440
	v_mul_f32_e64 v19, |v253|, -v65
	v_add_f32_e32 v253, 4.0, v239
	v_mul_f32_e64 v20, |v253|, -v65
	v_add_f32_e32 v253, 0x40a00000, v239
	v_mul_f32_e64 v21, |v253|, -v65
	v_add_f32_e32 v253, 0x40c00000, v239
	v_mul_f32_e64 v22, |v253|, -v65
	v_add_f32_e32 v253, 0x40e00000, v239
	v_mul_f32_e64 v23, |v253|, -v65
	s_waitcnt lgkmcnt(3)
	v_mfma_f32_32x32x16_bf16 v[98:113], v[218:221], v[122:125], v[98:113]
	ds_read_b128 v[218:221], v234 offset:17472
	v_add_f32_e32 v253, 0x41800000, v239
	v_mul_f32_e64 v24, |v253|, -v65
	v_add_f32_e32 v253, 0x41880000, v239
	v_mul_f32_e64 v25, |v253|, -v65
	v_add_f32_e32 v253, 0x41900000, v239
	v_mul_f32_e64 v26, |v253|, -v65
	v_add_f32_e32 v253, 0x41980000, v239
	v_mul_f32_e64 v27, |v253|, -v65
	v_add_f32_e32 v253, 0x41a00000, v239
	s_waitcnt lgkmcnt(3)
	v_mfma_f32_32x32x16_bf16 v[98:113], v[222:225], v[126:129], v[98:113]
	ds_read_b128 v[222:225], v234 offset:17504
	v_mul_f32_e64 v28, |v253|, -v65
	v_add_f32_e32 v253, 0x41a80000, v239
	v_mul_f32_e64 v29, |v253|, -v65
	v_add_f32_e32 v253, 0x41b00000, v239
	v_mul_f32_e64 v30, |v253|, -v65
	v_add_f32_e32 v253, 0x41b80000, v239
	v_mul_f32_e64 v31, |v253|, -v65
	s_waitcnt lgkmcnt(3)
	s_nop 0
	v_mfma_f32_32x32x16_bf16 v[16:31], v[210:213], v[114:117], v[16:31]
	ds_read_b128 v[210:213], v234 offset:26112
	s_add_i32 s2, s11, 96
	v_cvt_f32_u32_e32 v236, s2
	v_add_f32_e32 v236, v185, v236
	v_mul_f32_e64 v0, |v236|, -v65
	v_add_f32_e32 v253, 1.0, v236
	v_mul_f32_e64 v1, |v253|, -v65
	v_add_f32_e32 v253, 2.0, v236
	v_mul_f32_e64 v2, |v253|, -v65
	v_add_f32_e32 v253, 0x40400000, v236
	s_waitcnt lgkmcnt(3)
	v_mfma_f32_32x32x16_bf16 v[16:31], v[214:217], v[118:121], v[16:31]
	ds_read_b128 v[214:217], v234 offset:26144
	v_mul_f32_e64 v3, |v253|, -v65
	v_add_f32_e32 v253, 4.0, v236
	v_mul_f32_e64 v4, |v253|, -v65
	v_add_f32_e32 v253, 0x40a00000, v236
	v_mul_f32_e64 v5, |v253|, -v65
	v_add_f32_e32 v253, 0x40c00000, v236
	v_mul_f32_e64 v6, |v253|, -v65
	v_add_f32_e32 v253, 0x40e00000, v236
	v_mul_f32_e64 v7, |v253|, -v65
	s_waitcnt lgkmcnt(3)
	v_mfma_f32_32x32x16_bf16 v[16:31], v[218:221], v[122:125], v[16:31]
	ds_read_b128 v[218:221], v234 offset:26176
	v_add_f32_e32 v253, 0x41800000, v236
	v_mul_f32_e64 v8, |v253|, -v65
	v_add_f32_e32 v253, 0x41880000, v236
	v_mul_f32_e64 v9, |v253|, -v65
	v_add_f32_e32 v253, 0x41900000, v236
	v_mul_f32_e64 v10, |v253|, -v65
	v_add_f32_e32 v253, 0x41980000, v236
	v_mul_f32_e64 v11, |v253|, -v65
	v_add_f32_e32 v253, 0x41a00000, v236
	s_waitcnt lgkmcnt(3)
	v_mfma_f32_32x32x16_bf16 v[16:31], v[222:225], v[126:129], v[16:31]
	ds_read_b128 v[222:225], v234 offset:26208
	v_mul_f32_e64 v12, |v253|, -v65
	v_add_f32_e32 v253, 0x41a80000, v236
	v_mul_f32_e64 v13, |v253|, -v65
	v_add_f32_e32 v253, 0x41b00000, v236
	v_mul_f32_e64 v14, |v253|, -v65
	v_add_f32_e32 v253, 0x41b80000, v236
	v_mul_f32_e64 v15, |v253|, -v65
	s_waitcnt lgkmcnt(3)
	s_nop 0
	v_mfma_f32_32x32x16_bf16 v[0:15], v[210:213], v[114:117], v[0:15]
	s_waitcnt lgkmcnt(2)
	v_mfma_f32_32x32x16_bf16 v[0:15], v[214:217], v[118:121], v[0:15]
	s_waitcnt lgkmcnt(1)
	v_mfma_f32_32x32x16_bf16 v[0:15], v[218:221], v[122:125], v[0:15]
	s_waitcnt lgkmcnt(0)
; __device__ __forceinline__ float fast_exp2(float x) { return __builtin_amdgcn_exp2f(x); }
; __device__ void da_unit(char* lds, const Params& p, int layer, int unit) {
;     ...
;             float mx = s[0];
; #pragma unroll
;             for (int e = 1; e < 16; ++e) mx = fmaxf(mx, s[e]);
;             mx += A;
;             mx = fmaxf(mx, __shfl_xor(mx, 32));
;             if (!__all(mx <= mrow + 8.0f)) {
;                 const float mnew = fmaxf(mrow, mx);
;                 const float alpha = fast_exp2(mrow - mnew);
; #pragma unroll
;                 for (int k = 0; k < 4; ++k) O[k] = O[k] * alpha;
;                 lrow *= alpha; mrow = mnew;
;             }
;             const float mm = mrow - A;
;             float ps = 0.f;
; #pragma unroll
;             for (int e = 0; e < 16; ++e) { s[e] = fast_exp2(s[e] - mm); ps += s[e]; }
;             lrow += ps;
;             bf16x8 pb[2];
; #pragma unroll
;             for (int sp = 0; sp < 2; ++sp) {
;                 u32x4 w;
;                 w.x = cvt_pk_bf16(s[8 * sp + 0], s[8 * sp + 1]); w.y = cvt_pk_bf16(s[8 * sp + 2], s[8 * sp + 3]);
;                 w.z = cvt_pk_bf16(s[8 * sp + 4], s[8 * sp + 5]); w.w = cvt_pk_bf16(s[8 * sp + 6], s[8 * sp + 7]);
;                 pb[sp] = __builtin_bit_cast(bf16x8, w);
;             }
; #pragma unroll
;             for (int sp = 0; sp < 2; ++sp)
; #pragma unroll
;                 for (int k = 0; k < 4; ++k) {
;                     const bf16x8 vf = *(const bf16x8*)(cV + (kb >> 1) * DA_VSUB + (32 * k + r) * DA_VP + (32 * (kb & 1) + 16 * sp + 8 * h2) * 2);
;                     O[k] = __builtin_amdgcn_mfma_f32_32x32x16_bf16(vf, pb[sp], O[k], 0, 0, 0);
;                 }
	v_mfma_f32_32x32x16_bf16 v[0:15], v[222:225], v[126:129], v[0:15]
	ds_read_b128 v[226:229], v235 offset:18496
	ds_read_b128 v[230:233], v235 offset:23104
	ds_read_b128 v[174:177], v235 offset:27712
	ds_read_b128 v[246:249], v235 offset:32320
	v_max_f32_e32 v241, v82, v83
	v_max3_f32 v241, v241, v84, v85
	v_max3_f32 v241, v241, v86, v87
	v_max3_f32 v241, v241, v88, v89
	v_max3_f32 v241, v241, v90, v91
	v_max3_f32 v241, v241, v92, v93
	v_max3_f32 v241, v241, v94, v95
	v_max3_f32 v241, v241, v96, v97
	v_max3_f32 v241, v241, v98, v99
	v_max3_f32 v241, v241, v100, v101
	v_max3_f32 v241, v241, v102, v103
	v_max3_f32 v241, v241, v104, v105
	v_max3_f32 v241, v241, v106, v107
	v_max3_f32 v241, v241, v108, v109
	v_max3_f32 v241, v241, v110, v111
	v_max3_f32 v241, v241, v112, v113
	v_max3_f32 v241, v241, v16, v17
	v_max3_f32 v241, v241, v18, v19
	v_max3_f32 v241, v241, v20, v21
	v_max3_f32 v241, v241, v22, v23
	v_max3_f32 v241, v241, v24, v25
	v_max3_f32 v241, v241, v26, v27
	v_max3_f32 v241, v241, v28, v29
	v_max3_f32 v241, v241, v30, v31
	v_max3_f32 v241, v241, v0, v1
	v_max3_f32 v241, v241, v2, v3
	v_max3_f32 v241, v241, v4, v5
	v_max3_f32 v241, v241, v6, v7
	v_max3_f32 v241, v241, v8, v9
	v_max3_f32 v241, v241, v10, v11
	v_max3_f32 v241, v241, v12, v13
	v_max3_f32 v241, v241, v14, v15
	ds_bpermute_b32 v242, v244, v241
	v_mov_b32_e32 v191, 0
	v_mov_b32_e32 v192, 0
	s_waitcnt lgkmcnt(0)
	v_max_f32_e32 v241, v241, v242
	v_max_f32_e32 v169, 0xf149f2ca, v241
	v_sub_f32_e32 v0, v0, v169
	v_sub_f32_e32 v1, v1, v169
	v_sub_f32_e32 v2, v2, v169
	v_sub_f32_e32 v3, v3, v169
	v_exp_f32_e32 v0, v0
	v_exp_f32_e32 v1, v1
	v_exp_f32_e32 v2, v2
	v_exp_f32_e32 v3, v3
	v_add_f32_e32 v191, v191, v0
	v_add_f32_e32 v192, v192, v1
	v_cvt_pk_bf16_f32 v194, v0, v1
	v_add_f32_e32 v191, v191, v2
	v_add_f32_e32 v192, v192, v3
	v_cvt_pk_bf16_f32 v195, v2, v3
	v_sub_f32_e32 v4, v4, v169
	v_sub_f32_e32 v5, v5, v169
	v_sub_f32_e32 v6, v6, v169
	v_sub_f32_e32 v7, v7, v169
	v_exp_f32_e32 v4, v4
	v_exp_f32_e32 v5, v5
	v_exp_f32_e32 v6, v6
	v_exp_f32_e32 v7, v7
	v_add_f32_e32 v191, v191, v4
	v_add_f32_e32 v192, v192, v5
	v_cvt_pk_bf16_f32 v196, v4, v5
	v_add_f32_e32 v191, v191, v6
	v_add_f32_e32 v192, v192, v7
	v_cvt_pk_bf16_f32 v197, v6, v7
	v_sub_f32_e32 v8, v8, v169
	v_sub_f32_e32 v9, v9, v169
	v_sub_f32_e32 v10, v10, v169
	v_sub_f32_e32 v11, v11, v169
	v_exp_f32_e32 v8, v8
	v_exp_f32_e32 v9, v9
	v_exp_f32_e32 v10, v10
	v_exp_f32_e32 v11, v11
	v_add_f32_e32 v191, v191, v8
	v_add_f32_e32 v192, v192, v9
	v_cvt_pk_bf16_f32 v198, v8, v9
	v_add_f32_e32 v191, v191, v10
	v_add_f32_e32 v192, v192, v11
	v_cvt_pk_bf16_f32 v199, v10, v11
	v_sub_f32_e32 v12, v12, v169
	v_sub_f32_e32 v13, v13, v169
	v_sub_f32_e32 v14, v14, v169
	v_sub_f32_e32 v15, v15, v169
	v_exp_f32_e32 v12, v12
	v_exp_f32_e32 v13, v13
	v_exp_f32_e32 v14, v14
	v_exp_f32_e32 v15, v15
	v_add_f32_e32 v191, v191, v12
	v_add_f32_e32 v192, v192, v13
	v_cvt_pk_bf16_f32 v200, v12, v13
	v_add_f32_e32 v191, v191, v14
	v_add_f32_e32 v192, v192, v15
	v_cvt_pk_bf16_f32 v201, v14, v15
	v_sub_f32_e32 v16, v16, v169
	v_sub_f32_e32 v17, v17, v169
	v_sub_f32_e32 v18, v18, v169
	v_sub_f32_e32 v19, v19, v169
	v_exp_f32_e32 v16, v16
	v_exp_f32_e32 v17, v17
	v_exp_f32_e32 v18, v18
	v_exp_f32_e32 v19, v19
	v_add_f32_e32 v191, v191, v16
	v_add_f32_e32 v192, v192, v17
	v_cvt_pk_bf16_f32 v202, v16, v17
	v_add_f32_e32 v191, v191, v18
	v_add_f32_e32 v192, v192, v19
	v_cvt_pk_bf16_f32 v203, v18, v19
	v_sub_f32_e32 v20, v20, v169
	v_sub_f32_e32 v21, v21, v169
	v_sub_f32_e32 v22, v22, v169
	v_sub_f32_e32 v23, v23, v169
	v_exp_f32_e32 v20, v20
	v_exp_f32_e32 v21, v21
	v_exp_f32_e32 v22, v22
	v_exp_f32_e32 v23, v23
	v_add_f32_e32 v191, v191, v20
	v_add_f32_e32 v192, v192, v21
	v_cvt_pk_bf16_f32 v204, v20, v21
	v_add_f32_e32 v191, v191, v22
	v_add_f32_e32 v192, v192, v23
	v_cvt_pk_bf16_f32 v205, v22, v23
	v_sub_f32_e32 v24, v24, v169
	v_sub_f32_e32 v25, v25, v169
	v_sub_f32_e32 v26, v26, v169
	v_sub_f32_e32 v27, v27, v169
	v_exp_f32_e32 v24, v24
	v_exp_f32_e32 v25, v25
	v_exp_f32_e32 v26, v26
	v_exp_f32_e32 v27, v27
	v_add_f32_e32 v191, v191, v24
	v_add_f32_e32 v192, v192, v25
	v_cvt_pk_bf16_f32 v206, v24, v25
	v_add_f32_e32 v191, v191, v26
	v_add_f32_e32 v192, v192, v27
	v_cvt_pk_bf16_f32 v207, v26, v27
	v_sub_f32_e32 v28, v28, v169
	v_sub_f32_e32 v29, v29, v169
	v_sub_f32_e32 v30, v30, v169
	v_sub_f32_e32 v31, v31, v169
	v_exp_f32_e32 v28, v28
	v_exp_f32_e32 v29, v29
	v_exp_f32_e32 v30, v30
	v_exp_f32_e32 v31, v31
	v_add_f32_e32 v191, v191, v28
	v_add_f32_e32 v192, v192, v29
	v_cvt_pk_bf16_f32 v208, v28, v29
	v_add_f32_e32 v191, v191, v30
	v_add_f32_e32 v192, v192, v31
	v_cvt_pk_bf16_f32 v209, v30, v31
	v_mfma_f32_32x32x16_bf16 v[48:63], v[226:229], v[194:197], 0
	ds_read_b128 v[226:229], v235 offset:18528
	v_sub_f32_e32 v98, v98, v169
	v_sub_f32_e32 v99, v99, v169
	v_sub_f32_e32 v100, v100, v169
	v_sub_f32_e32 v101, v101, v169
	v_exp_f32_e32 v98, v98
	v_exp_f32_e32 v99, v99
	v_exp_f32_e32 v100, v100
	v_exp_f32_e32 v101, v101
	v_mfma_f32_32x32x16_bf16 v[32:47], v[230:233], v[194:197], 0
	ds_read_b128 v[230:233], v235 offset:23136
	v_add_f32_e32 v191, v191, v98
	v_add_f32_e32 v192, v192, v99
	v_cvt_pk_bf16_f32 v210, v98, v99
	v_add_f32_e32 v191, v191, v100
	v_add_f32_e32 v192, v192, v101
	v_cvt_pk_bf16_f32 v211, v100, v101
	v_sub_f32_e32 v102, v102, v169
	v_sub_f32_e32 v103, v103, v169
	v_sub_f32_e32 v104, v104, v169
	v_sub_f32_e32 v105, v105, v169
	v_exp_f32_e32 v102, v102
	v_mfma_f32_32x32x16_bf16 v[16:31], v[174:177], v[194:197], 0
	ds_read_b128 v[174:177], v235 offset:27744
	v_exp_f32_e32 v103, v103
	v_exp_f32_e32 v104, v104
	v_exp_f32_e32 v105, v105
	v_add_f32_e32 v191, v191, v102
	v_add_f32_e32 v192, v192, v103
	v_cvt_pk_bf16_f32 v212, v102, v103
	v_add_f32_e32 v191, v191, v104
	v_add_f32_e32 v192, v192, v105
	v_cvt_pk_bf16_f32 v213, v104, v105
	v_mfma_f32_32x32x16_bf16 v[0:15], v[246:249], v[194:197], 0
	ds_read_b128 v[246:249], v235 offset:32352
	v_sub_f32_e32 v106, v106, v169
	v_sub_f32_e32 v107, v107, v169
	v_sub_f32_e32 v108, v108, v169
	v_sub_f32_e32 v109, v109, v169
	v_exp_f32_e32 v106, v106
	v_exp_f32_e32 v107, v107
	v_exp_f32_e32 v108, v108
	v_exp_f32_e32 v109, v109
	s_waitcnt lgkmcnt(3)
; __device__ void da_unit(char* lds, const Params& p, int layer, int unit) {
;     ...
; #pragma unroll
;             for (int sp = 0; sp < 2; ++sp)
; #pragma unroll
;                 for (int k = 0; k < 4; ++k) {
;                     const bf16x8 vf = *(const bf16x8*)(cV + (kb >> 1) * DA_VSUB + (32 * k + r) * DA_VP + (32 * (kb & 1) + 16 * sp + 8 * h2) * 2);
;                     O[k] = __builtin_amdgcn_mfma_f32_32x32x16_bf16(vf, pb[sp], O[k], 0, 0, 0);
;                 }
;         }
;         if (it + 1 < NT) {
; #pragma unroll
;             for (int j = 0; j < 4; ++j) {
;                 *(u32x4*)(nK + (kr_ + 32 * j) * DA_KP + kc_ * 16) = rk[j];
;                 *(u32x4*)(nK + DA_KBYTES + (j >> 1) * DA_VSUB + (vr_ + 64 * (j & 1)) * DA_VP + vc_ * 16) = rv[j];
;             }
;         }
;         __syncthreads();
	v_mfma_f32_32x32x16_bf16 v[48:63], v[226:229], v[198:201], v[48:63]
	ds_read_b128 v[226:229], v235 offset:18432
	v_add_f32_e32 v191, v191, v106
	v_add_f32_e32 v192, v192, v107
	v_cvt_pk_bf16_f32 v214, v106, v107
	v_add_f32_e32 v191, v191, v108
	v_add_f32_e32 v192, v192, v109
	v_cvt_pk_bf16_f32 v215, v108, v109
	s_waitcnt lgkmcnt(3)
	v_mfma_f32_32x32x16_bf16 v[32:47], v[230:233], v[198:201], v[32:47]
	ds_read_b128 v[230:233], v235 offset:23040
	v_sub_f32_e32 v110, v110, v169
	v_sub_f32_e32 v111, v111, v169
	v_sub_f32_e32 v112, v112, v169
	v_sub_f32_e32 v113, v113, v169
	v_exp_f32_e32 v110, v110
	s_waitcnt lgkmcnt(3)
	v_mfma_f32_32x32x16_bf16 v[16:31], v[174:177], v[198:201], v[16:31]
	ds_read_b128 v[174:177], v235 offset:27648
	v_exp_f32_e32 v111, v111
	v_exp_f32_e32 v112, v112
	v_exp_f32_e32 v113, v113
	s_waitcnt lgkmcnt(3)
	v_mfma_f32_32x32x16_bf16 v[0:15], v[246:249], v[198:201], v[0:15]
	ds_read_b128 v[246:249], v235 offset:32256
	v_add_f32_e32 v191, v191, v110
	v_add_f32_e32 v192, v192, v111
	v_cvt_pk_bf16_f32 v216, v110, v111
	v_add_f32_e32 v191, v191, v112
	v_add_f32_e32 v192, v192, v113
	v_cvt_pk_bf16_f32 v217, v112, v113
	s_waitcnt lgkmcnt(3)
	v_mfma_f32_32x32x16_bf16 v[48:63], v[226:229], v[202:205], v[48:63]
	ds_read_b128 v[226:229], v235 offset:18464
	v_sub_f32_e32 v82, v82, v169
	v_sub_f32_e32 v83, v83, v169
	v_sub_f32_e32 v84, v84, v169
	v_sub_f32_e32 v85, v85, v169
	v_exp_f32_e32 v82, v82
	v_exp_f32_e32 v83, v83
	v_exp_f32_e32 v84, v84
	v_exp_f32_e32 v85, v85
	s_waitcnt lgkmcnt(3)
	v_mfma_f32_32x32x16_bf16 v[32:47], v[230:233], v[202:205], v[32:47]
	ds_read_b128 v[230:233], v235 offset:23072
	v_add_f32_e32 v191, v191, v82
	v_add_f32_e32 v192, v192, v83
	v_cvt_pk_bf16_f32 v218, v82, v83
	v_add_f32_e32 v191, v191, v84
	v_add_f32_e32 v192, v192, v85
	v_cvt_pk_bf16_f32 v219, v84, v85
	v_sub_f32_e32 v86, v86, v169
	v_sub_f32_e32 v87, v87, v169
	v_sub_f32_e32 v88, v88, v169
	v_sub_f32_e32 v89, v89, v169
	v_exp_f32_e32 v86, v86
	s_waitcnt lgkmcnt(3)
	v_mfma_f32_32x32x16_bf16 v[16:31], v[174:177], v[202:205], v[16:31]
	ds_read_b128 v[174:177], v235 offset:27680
	v_exp_f32_e32 v87, v87
	v_exp_f32_e32 v88, v88
	v_exp_f32_e32 v89, v89
	v_add_f32_e32 v191, v191, v86
	v_add_f32_e32 v192, v192, v87
	v_cvt_pk_bf16_f32 v220, v86, v87
	v_add_f32_e32 v191, v191, v88
	v_add_f32_e32 v192, v192, v89
	v_cvt_pk_bf16_f32 v221, v88, v89
	s_waitcnt lgkmcnt(3)
	v_mfma_f32_32x32x16_bf16 v[0:15], v[246:249], v[202:205], v[0:15]
	ds_read_b128 v[246:249], v235 offset:32288
	v_sub_f32_e32 v90, v90, v169
	v_sub_f32_e32 v91, v91, v169
	v_sub_f32_e32 v92, v92, v169
	v_sub_f32_e32 v93, v93, v169
	v_exp_f32_e32 v90, v90
	v_exp_f32_e32 v91, v91
	v_exp_f32_e32 v92, v92
	v_exp_f32_e32 v93, v93
	s_waitcnt lgkmcnt(3)
	v_mfma_f32_32x32x16_bf16 v[48:63], v[226:229], v[206:209], v[48:63]
	ds_read_b128 v[226:229], v235 offset:64
	v_add_f32_e32 v191, v191, v90
	v_add_f32_e32 v192, v192, v91
	v_cvt_pk_bf16_f32 v222, v90, v91
	v_add_f32_e32 v191, v191, v92
	v_add_f32_e32 v192, v192, v93
	v_cvt_pk_bf16_f32 v223, v92, v93
	s_waitcnt lgkmcnt(3)
	v_mfma_f32_32x32x16_bf16 v[32:47], v[230:233], v[206:209], v[32:47]
	ds_read_b128 v[230:233], v235 offset:4672
	v_sub_f32_e32 v94, v94, v169
	v_sub_f32_e32 v95, v95, v169
	v_sub_f32_e32 v96, v96, v169
	v_sub_f32_e32 v97, v97, v169
	v_exp_f32_e32 v94, v94
	s_waitcnt lgkmcnt(3)
	v_mfma_f32_32x32x16_bf16 v[16:31], v[174:177], v[206:209], v[16:31]
	ds_read_b128 v[174:177], v235 offset:9280
	v_exp_f32_e32 v95, v95
	v_exp_f32_e32 v96, v96
	v_exp_f32_e32 v97, v97
	s_waitcnt lgkmcnt(3)
	v_mfma_f32_32x32x16_bf16 v[0:15], v[246:249], v[206:209], v[0:15]
	ds_read_b128 v[246:249], v235 offset:13888
	v_add_f32_e32 v191, v191, v94
	v_add_f32_e32 v192, v192, v95
	v_cvt_pk_bf16_f32 v224, v94, v95
	v_add_f32_e32 v191, v191, v96
	v_add_f32_e32 v192, v192, v97
	v_cvt_pk_bf16_f32 v225, v96, v97
	s_waitcnt lgkmcnt(3)
	v_mfma_f32_32x32x16_bf16 v[48:63], v[226:229], v[210:213], v[48:63]
	ds_read_b128 v[226:229], v235 offset:96
	s_mov_b32 s2, 0x11800
	v_add3_u32 v158, s2, v180, v182
	v_add3_u32 v242, s2, v183, v181
	s_waitcnt vmcnt(7)
	ds_write_b128 v158, v[130:133] offset:0
	s_waitcnt lgkmcnt(4)
	v_mfma_f32_32x32x16_bf16 v[32:47], v[230:233], v[210:213], v[32:47]
	ds_read_b128 v[230:233], v235 offset:4704
	s_waitcnt vmcnt(6)
	ds_write_b128 v158, v[134:137] offset:8704
	s_waitcnt lgkmcnt(5)
	v_mfma_f32_32x32x16_bf16 v[16:31], v[174:177], v[210:213], v[16:31]
	ds_read_b128 v[174:177], v235 offset:9312
	s_waitcnt vmcnt(5)
	ds_write_b128 v158, v[138:141] offset:17408
	s_waitcnt lgkmcnt(6)
	v_mfma_f32_32x32x16_bf16 v[0:15], v[246:249], v[210:213], v[0:15]
	ds_read_b128 v[246:249], v235 offset:13920
	s_waitcnt vmcnt(4)
	ds_write_b128 v158, v[142:145] offset:26112
	s_waitcnt lgkmcnt(7)
	v_mfma_f32_32x32x16_bf16 v[48:63], v[226:229], v[214:217], v[48:63]
	ds_read_b128 v[226:229], v235 offset:0
	s_waitcnt vmcnt(3)
	ds_write_b128 v242, v[66:69] offset:34816
	s_waitcnt lgkmcnt(7)
	v_mfma_f32_32x32x16_bf16 v[32:47], v[230:233], v[214:217], v[32:47]
	ds_read_b128 v[230:233], v235 offset:4608
	s_waitcnt vmcnt(2)
	ds_write_b128 v242, v[70:73] offset:44032
	s_waitcnt lgkmcnt(7)
	v_mfma_f32_32x32x16_bf16 v[16:31], v[174:177], v[214:217], v[16:31]
	ds_read_b128 v[174:177], v235 offset:9216
	s_waitcnt vmcnt(1)
	ds_write_b128 v242, v[74:77] offset:53248
	s_waitcnt lgkmcnt(7)
	v_mfma_f32_32x32x16_bf16 v[0:15], v[246:249], v[214:217], v[0:15]
	ds_read_b128 v[246:249], v235 offset:13824
	s_waitcnt vmcnt(0)
	ds_write_b128 v242, v[78:81] offset:62464
	s_waitcnt lgkmcnt(7)
	v_mfma_f32_32x32x16_bf16 v[48:63], v[226:229], v[218:221], v[48:63]
	ds_read_b128 v[226:229], v235 offset:32
	s_waitcnt lgkmcnt(6)
	v_mfma_f32_32x32x16_bf16 v[32:47], v[230:233], v[218:221], v[32:47]
	ds_read_b128 v[230:233], v235 offset:4640
	s_waitcnt lgkmcnt(5)
	v_mfma_f32_32x32x16_bf16 v[16:31], v[174:177], v[218:221], v[16:31]
	ds_read_b128 v[174:177], v235 offset:9248
	s_waitcnt lgkmcnt(4)
	v_mfma_f32_32x32x16_bf16 v[0:15], v[246:249], v[218:221], v[0:15]
	ds_read_b128 v[246:249], v235 offset:13856
	s_waitcnt lgkmcnt(3)
	v_mfma_f32_32x32x16_bf16 v[48:63], v[226:229], v[222:225], v[48:63]
	s_waitcnt lgkmcnt(2)
	v_mfma_f32_32x32x16_bf16 v[32:47], v[230:233], v[222:225], v[32:47]
	s_waitcnt lgkmcnt(1)
	v_mfma_f32_32x32x16_bf16 v[16:31], v[174:177], v[222:225], v[16:31]
	s_waitcnt lgkmcnt(0)
	v_mfma_f32_32x32x16_bf16 v[0:15], v[246:249], v[222:225], v[0:15]
	v_add_f32_e32 v193, v191, v192
	s_sub_i32 s9, 16, s14
	s_waitcnt lgkmcnt(0)
	s_barrier
; __device__ void da_unit(char* lds, const Params& p, int layer, int unit) {
;     ...
;     for (int e = 0; e < 16; ++e) Bs[e] = -slope2 * (float)(16 * (e >> 3) + (e & 7));
;     float mrow = -1e30f, lrow = 0.f;
;     ...
; #pragma unroll
;     for (int e = 0; e < 16; ++e) Bs[e] = -Bs[e];
;     for (int it = NT - qb; it < NT; ++it) {
	v_mul_f32_e32 v66, 0x80000000, v65
	v_mul_f32_e32 v68, -2.0, v65
	v_mul_f32_e32 v69, 0xc0400000, v65
	v_mul_f32_e32 v70, -4.0, v65
	v_mul_f32_e32 v71, 0xc0a00000, v65
	v_mul_f32_e32 v72, 0xc0c00000, v65
	v_mul_f32_e32 v73, 0xc0e00000, v65
	v_mul_f32_e32 v74, 0xc1800000, v65
	v_mul_f32_e32 v75, 0xc1880000, v65
	v_mul_f32_e32 v76, 0xc1900000, v65
	v_mul_f32_e32 v77, 0xc1980000, v65
	v_mul_f32_e32 v78, 0xc1a00000, v65
	v_mul_f32_e32 v79, 0xc1a80000, v65
	v_mul_f32_e32 v80, 0xc1b00000, v65
	v_mul_f32_e32 v81, 0xc1b80000, v65
	v_xor_b32_e32 v67, 0x80000000, v65
	v_mul_f32_e32 v64, 0xc2000000, v65
	v_mov_b32_e32 v250, v65
	v_mov_b32_e32 v191, 0
	v_mov_b32_e32 v192, 0
	v_mov_b32_e32 v202, 0
	v_mov_b32_e32 v203, 0
	v_mov_b32_e32 v204, 0
	v_mov_b32_e32 v205, 0
	v_mov_b32_e32 v206, 0
	v_mov_b32_e32 v207, 0
	v_mov_b32_e32 v208, 0
	v_mov_b32_e32 v209, 0
	s_cmp_lg_u32 s9, 1
	s_cbranch_scc1 .Lda_p_noflip
	v_xor_b32_e32 v66, 0x80000000, v66
	v_xor_b32_e32 v67, 0x80000000, v67
	v_xor_b32_e32 v68, 0x80000000, v68
	v_xor_b32_e32 v69, 0x80000000, v69
	v_xor_b32_e32 v70, 0x80000000, v70
	v_xor_b32_e32 v71, 0x80000000, v71
	v_xor_b32_e32 v72, 0x80000000, v72
	v_xor_b32_e32 v73, 0x80000000, v73
	v_xor_b32_e32 v74, 0x80000000, v74
	v_xor_b32_e32 v75, 0x80000000, v75
	v_xor_b32_e32 v76, 0x80000000, v76
	v_xor_b32_e32 v77, 0x80000000, v77
	v_xor_b32_e32 v78, 0x80000000, v78
	v_xor_b32_e32 v79, 0x80000000, v79
	v_xor_b32_e32 v80, 0x80000000, v80
	v_xor_b32_e32 v81, 0x80000000, v81

; __device__ void da_unit(char* lds, const Params& p, int layer, int unit) {
;     ...
;     for (int it = 1; it < NT - qb; ++it) {
;         const int kt = tile_of(it);
;         const char* cK = lds + (it & 1) * DA_STAGE;
;         const char* cV = cK + DA_KBYTES;
;         char* nK = lds + ((it + 1) & 1) * DA_STAGE;
;         const int tn = tile_of(it + 1 < NT ? it + 1 : it);
;         if (it + 1 < NT) {
; #pragma unroll
;             for (int j = 0; j < 4; ++j) rk[j] = *(const u32x4*)(Kg + (size_t)tn * 16384 + j * 4096);
;         }
.Lda_noflip:
	s_add_i32 s0, s14, s4
	s_sub_i32 s1, 15, s4
	s_cmp_lt_u32 s4, s9
	s_cselect_b32 s10, s0, s1
	s_lshl_b32 s11, s10, 7
	s_add_i32 s16, s4, 1
	s_add_i32 s0, s14, s16
	s_sub_i32 s1, 15, s16
	s_cmp_lt_u32 s16, s9
	s_cselect_b32 s0, s0, s1
	s_max_i32 s0, s0, 0
	s_add_i32 s16, s4, 2
	s_add_i32 s3, s14, s16
	s_sub_i32 s1, 15, s16
	s_cmp_lt_u32 s16, s9
	s_cselect_b32 s3, s3, s1
	s_max_i32 s3, s3, 0
	s_bitcmp1_b32 s4, 0
	s_cselect_b32 s17, 0x11800, 0
	s_sub_i32 s5, 0x11800, s17
	s_add_i32 s1, s17, s8
	s_add_i32 s2, s17, 0x8800
	v_add3_u32 v234, s1, v186, v152
	v_add3_u32 v235, s2, v152, v154
	s_add_i32 s1, s5, s8
	s_add_i32 s2, s5, 0x8800
	v_add3_u32 v236, s1, v186, v152
	v_add3_u32 v178, s2, v152, v154
	v_cvt_f32_u32_e32 v242, s11
	v_add_f32_e32 v242, v185, v242
	v_fma_f32 v239, v242, v250, v169
	v_fma_f32 v253, v242, -v250, v64
	v_sub_f32_e32 v241, v169, v253
	v_mfma_f32_32x32x16_bf16 v[98:113], v[210:213], v[114:117], v[66:81]
	ds_read_b128 v[210:213], v234 offset:17408
	v_sub_f32_e32 v82, v82, v239
	v_sub_f32_e32 v83, v83, v239
	v_sub_f32_e32 v84, v84, v239
	v_sub_f32_e32 v85, v85, v239
	v_exp_f32_e32 v82, v82
	v_mfma_f32_32x32x16_bf16 v[48:63], v[226:229], v[202:205], v[48:63]
	ds_read_b128 v[226:229], v178 offset:18528
	v_exp_f32_e32 v83, v83
	v_exp_f32_e32 v84, v84
	v_exp_f32_e32 v85, v85
	v_mfma_f32_32x32x16_bf16 v[32:47], v[230:233], v[202:205], v[32:47]
	ds_read_b128 v[230:233], v178 offset:23136
	v_add_f32_e32 v191, v191, v82
	v_add_f32_e32 v192, v192, v83
	v_cvt_pk_bf16_f32 v194, v82, v83
	v_add_f32_e32 v191, v191, v84
	v_add_f32_e32 v192, v192, v85
	v_cvt_pk_bf16_f32 v195, v84, v85
	v_mfma_f32_32x32x16_bf16 v[98:113], v[214:217], v[118:121], v[98:113]
	ds_read_b128 v[214:217], v234 offset:17440
	v_sub_f32_e32 v86, v86, v239
	v_sub_f32_e32 v87, v87, v239
	v_sub_f32_e32 v88, v88, v239
	v_sub_f32_e32 v89, v89, v239
	v_exp_f32_e32 v86, v86
	v_mfma_f32_32x32x16_bf16 v[16:31], v[174:177], v[202:205], v[16:31]
	ds_read_b128 v[174:177], v178 offset:27744
	v_exp_f32_e32 v87, v87
	v_exp_f32_e32 v88, v88
	v_exp_f32_e32 v89, v89
	v_mfma_f32_32x32x16_bf16 v[0:15], v[246:249], v[202:205], v[0:15]
	ds_read_b128 v[246:249], v178 offset:32352
	v_add_f32_e32 v191, v191, v86
	v_add_f32_e32 v192, v192, v87
	v_cvt_pk_bf16_f32 v196, v86, v87
	v_add_f32_e32 v191, v191, v88
	v_add_f32_e32 v192, v192, v89
	v_cvt_pk_bf16_f32 v197, v88, v89
	v_mfma_f32_32x32x16_bf16 v[98:113], v[218:221], v[122:125], v[98:113]
	ds_read_b128 v[218:221], v234 offset:17472
	v_sub_f32_e32 v90, v90, v239
	v_sub_f32_e32 v91, v91, v239
	v_sub_f32_e32 v92, v92, v239
	v_sub_f32_e32 v93, v93, v239
	v_exp_f32_e32 v90, v90
	s_waitcnt lgkmcnt(5)
	v_mfma_f32_32x32x16_bf16 v[48:63], v[226:229], v[206:209], v[48:63]
	ds_read_b128 v[226:229], v235 offset:0
	v_exp_f32_e32 v91, v91
	v_exp_f32_e32 v92, v92
	v_exp_f32_e32 v93, v93
	s_waitcnt lgkmcnt(5)
	v_mfma_f32_32x32x16_bf16 v[32:47], v[230:233], v[206:209], v[32:47]
	ds_read_b128 v[230:233], v235 offset:4608
	v_add_f32_e32 v191, v191, v90
	v_add_f32_e32 v192, v192, v91
	v_cvt_pk_bf16_f32 v198, v90, v91
	v_add_f32_e32 v191, v191, v92
	v_add_f32_e32 v192, v192, v93
	v_cvt_pk_bf16_f32 v199, v92, v93
	v_mfma_f32_32x32x16_bf16 v[98:113], v[222:225], v[126:129], v[98:113]
	ds_read_b128 v[222:225], v234 offset:17504
	v_sub_f32_e32 v94, v94, v239
	v_sub_f32_e32 v95, v95, v239
	v_sub_f32_e32 v96, v96, v239
	v_sub_f32_e32 v97, v97, v239
	v_exp_f32_e32 v94, v94
	s_waitcnt lgkmcnt(5)
	v_mfma_f32_32x32x16_bf16 v[16:31], v[174:177], v[206:209], v[16:31]
	ds_read_b128 v[174:177], v235 offset:9216
	v_exp_f32_e32 v95, v95
	v_exp_f32_e32 v96, v96
	v_exp_f32_e32 v97, v97
	s_waitcnt lgkmcnt(5)
	v_mfma_f32_32x32x16_bf16 v[0:15], v[246:249], v[206:209], v[0:15]
	ds_read_b128 v[246:249], v235 offset:13824
	v_add_f32_e32 v191, v191, v94
	v_add_f32_e32 v192, v192, v95
	v_cvt_pk_bf16_f32 v200, v94, v95
	v_add_f32_e32 v191, v191, v96
	v_add_f32_e32 v192, v192, v97
	v_cvt_pk_bf16_f32 v201, v96, v97
	s_waitcnt lgkmcnt(0)
	s_barrier
	v_mfma_f32_32x32x16_bf16 v[82:97], v[210:213], v[114:117], v[66:81]
	ds_read_b128 v[210:213], v234 offset:26112
	v_add3_u32 v158, s5, v180, v182
	v_sub_f32_e32 v98, v98, v241
	v_sub_f32_e32 v99, v99, v241
	v_sub_f32_e32 v100, v100, v241
	v_sub_f32_e32 v101, v101, v241
	v_exp_f32_e32 v98, v98
	v_mfma_f32_32x32x16_bf16 v[48:63], v[226:229], v[194:197], v[48:63]
	ds_read_b128 v[226:229], v235 offset:32
	s_waitcnt vmcnt(3)
	ds_write_b128 v158, v[130:133] offset:0
	s_lshl_b32 s18, s0, 15
	s_mov_b32 s19, 0
	v_lshl_add_u64 v[156:157], v[150:151], 0, s[18:19]
	global_load_dwordx4 v[130:133], v[156:157], off
	v_exp_f32_e32 v99, v99
	v_exp_f32_e32 v100, v100
	v_exp_f32_e32 v101, v101
	v_mfma_f32_32x32x16_bf16 v[32:47], v[230:233], v[194:197], v[32:47]
	ds_read_b128 v[230:233], v235 offset:4640
	v_add_f32_e32 v191, v191, v98
	v_add_f32_e32 v192, v192, v99
	v_cvt_pk_bf16_f32 v202, v98, v99
	v_add_f32_e32 v191, v191, v100
	v_add_f32_e32 v192, v192, v101
	v_cvt_pk_bf16_f32 v203, v100, v101
	v_mfma_f32_32x32x16_bf16 v[82:97], v[214:217], v[118:121], v[82:97]
	ds_read_b128 v[214:217], v234 offset:26144
	s_waitcnt vmcnt(3)
	ds_write_b128 v158, v[134:137] offset:8704
	s_add_u32 s18, s18, 0x2000
	v_lshl_add_u64 v[156:157], v[150:151], 0, s[18:19]
	global_load_dwordx4 v[134:137], v[156:157], off
	v_sub_f32_e32 v102, v102, v241
	v_sub_f32_e32 v103, v103, v241
	v_sub_f32_e32 v104, v104, v241
	v_sub_f32_e32 v105, v105, v241
	v_exp_f32_e32 v102, v102
	v_mfma_f32_32x32x16_bf16 v[16:31], v[174:177], v[194:197], v[16:31]
	ds_read_b128 v[174:177], v235 offset:9248
	v_exp_f32_e32 v103, v103
	v_exp_f32_e32 v104, v104
	v_exp_f32_e32 v105, v105
	v_mfma_f32_32x32x16_bf16 v[0:15], v[246:249], v[194:197], v[0:15]
	ds_read_b128 v[246:249], v235 offset:13856
	s_waitcnt vmcnt(3)
; __device__ void da_unit(char* lds, const Params& p, int layer, int unit) {
;     ...
;         DA_FAST_HALF(Bs, -slope2, 0)
;         if (it + 1 < NT) {
; #pragma unroll
;             for (int j = 0; j < 4; ++j) *(u32x4*)(nK + (kr_ + 32 * j) * DA_KP + kc_ * 16) = rk[j];
; #pragma unroll
;             for (int j = 0; j < 4; ++j) rk[j] = *(const u32x4*)(Vg + (size_t)tn * 16384 + j * 4096);
;         }
;         DA_FAST_HALF(Bs, -slope2, 1)
;     ...
;         if (it + 1 < NT) {
; #pragma unroll
;             for (int j = 0; j < 4; ++j) *(u32x4*)(nK + DA_KBYTES + (j >> 1) * DA_VSUB + (vr_ + 64 * (j & 1)) * DA_VP + vc_ * 16) = rk[j];
;         }
;         __syncthreads();
;     }
; #pragma unroll
;     for (int e = 0; e < 16; ++e) Bs[e] = -Bs[e];
;     for (int it = NT - qb; it < NT; ++it) {
;         const int kt = tile_of(it);
;         const char* cK = lds + (it & 1) * DA_STAGE;
;         const char* cV = cK + DA_KBYTES;
;         char* nK = lds + ((it + 1) & 1) * DA_STAGE;
;         const int tn = tile_of(it + 1 < NT ? it + 1 : it);
	ds_write_b128 v158, v[138:141] offset:17408
	s_add_u32 s18, s18, 0x2000
	v_lshl_add_u64 v[156:157], v[150:151], 0, s[18:19]
	global_load_dwordx4 v[138:141], v[156:157], off
	v_add_f32_e32 v191, v191, v102
	v_add_f32_e32 v192, v192, v103
	v_cvt_pk_bf16_f32 v204, v102, v103
	v_add_f32_e32 v191, v191, v104
	v_add_f32_e32 v192, v192, v105
	v_cvt_pk_bf16_f32 v205, v104, v105
	v_mfma_f32_32x32x16_bf16 v[82:97], v[218:221], v[122:125], v[82:97]
	ds_read_b128 v[218:221], v234 offset:26176
	v_sub_f32_e32 v106, v106, v241
	v_sub_f32_e32 v107, v107, v241
	v_sub_f32_e32 v108, v108, v241
	v_sub_f32_e32 v109, v109, v241
	v_exp_f32_e32 v106, v106
	s_waitcnt lgkmcnt(8)
	v_mfma_f32_32x32x16_bf16 v[48:63], v[226:229], v[198:201], v[48:63]
	ds_read_b128 v[226:229], v235 offset:64
	s_waitcnt vmcnt(3)
	ds_write_b128 v158, v[142:145] offset:26112
	s_add_u32 s18, s18, 0x2000
	v_lshl_add_u64 v[156:157], v[150:151], 0, s[18:19]
	global_load_dwordx4 v[142:145], v[156:157], off
	v_exp_f32_e32 v107, v107
	v_exp_f32_e32 v108, v108
	v_exp_f32_e32 v109, v109
	s_waitcnt lgkmcnt(8)
	v_mfma_f32_32x32x16_bf16 v[32:47], v[230:233], v[198:201], v[32:47]
	ds_read_b128 v[230:233], v235 offset:4672
	v_add_f32_e32 v191, v191, v106
	v_add_f32_e32 v192, v192, v107
	v_cvt_pk_bf16_f32 v206, v106, v107
	v_add_f32_e32 v191, v191, v108
	v_add_f32_e32 v192, v192, v109
	v_cvt_pk_bf16_f32 v207, v108, v109
	v_mfma_f32_32x32x16_bf16 v[82:97], v[222:225], v[126:129], v[82:97]
	ds_read_b128 v[222:225], v234 offset:26208
	v_sub_f32_e32 v110, v110, v241
	v_sub_f32_e32 v111, v111, v241
	v_sub_f32_e32 v112, v112, v241
	v_sub_f32_e32 v113, v113, v241
	v_exp_f32_e32 v110, v110
	s_waitcnt lgkmcnt(7)
	v_mfma_f32_32x32x16_bf16 v[16:31], v[174:177], v[198:201], v[16:31]
	ds_read_b128 v[174:177], v235 offset:9280
	v_exp_f32_e32 v111, v111
	v_exp_f32_e32 v112, v112
	v_exp_f32_e32 v113, v113
	s_waitcnt lgkmcnt(7)
	v_mfma_f32_32x32x16_bf16 v[0:15], v[246:249], v[198:201], v[0:15]
	ds_read_b128 v[246:249], v235 offset:13888
	v_add_f32_e32 v191, v191, v110
	v_add_f32_e32 v192, v192, v111
	v_cvt_pk_bf16_f32 v208, v110, v111
	v_add_f32_e32 v191, v191, v112
	v_add_f32_e32 v192, v192, v113
	v_cvt_pk_bf16_f32 v209, v112, v113
	s_or_b32 s2, s11, 64
	v_cvt_f32_u32_e32 v242, s2
	v_add_f32_e32 v242, v185, v242
	v_fma_f32 v239, v242, v250, v169
	v_fma_f32 v253, v242, -v250, v64
	v_sub_f32_e32 v241, v169, v253
	v_mfma_f32_32x32x16_bf16 v[98:113], v[210:213], v[114:117], v[66:81]
	v_sub_f32_e32 v82, v82, v239
	v_sub_f32_e32 v83, v83, v239
	v_sub_f32_e32 v84, v84, v239
	v_sub_f32_e32 v85, v85, v239
	v_exp_f32_e32 v82, v82
	s_waitcnt lgkmcnt(5)
	v_mfma_f32_32x32x16_bf16 v[48:63], v[226:229], v[202:205], v[48:63]
	ds_read_b128 v[226:229], v235 offset:96
	v_exp_f32_e32 v83, v83
	v_exp_f32_e32 v84, v84
	v_exp_f32_e32 v85, v85
	s_waitcnt lgkmcnt(4)
	v_mfma_f32_32x32x16_bf16 v[32:47], v[230:233], v[202:205], v[32:47]
	ds_read_b128 v[230:233], v235 offset:4704
	v_add_f32_e32 v191, v191, v82
	v_add_f32_e32 v192, v192, v83
	v_cvt_pk_bf16_f32 v194, v82, v83
	v_add_f32_e32 v191, v191, v84
	v_add_f32_e32 v192, v192, v85
	v_cvt_pk_bf16_f32 v195, v84, v85
	v_mfma_f32_32x32x16_bf16 v[98:113], v[214:217], v[118:121], v[98:113]
	v_sub_f32_e32 v86, v86, v239
	v_sub_f32_e32 v87, v87, v239
	v_sub_f32_e32 v88, v88, v239
	v_sub_f32_e32 v89, v89, v239
	v_exp_f32_e32 v86, v86
	s_waitcnt lgkmcnt(3)
	v_mfma_f32_32x32x16_bf16 v[16:31], v[174:177], v[202:205], v[16:31]
	ds_read_b128 v[174:177], v235 offset:9312
	v_exp_f32_e32 v87, v87
	v_exp_f32_e32 v88, v88
	v_exp_f32_e32 v89, v89
	s_waitcnt lgkmcnt(3)
	v_mfma_f32_32x32x16_bf16 v[0:15], v[246:249], v[202:205], v[0:15]
	ds_read_b128 v[246:249], v235 offset:13920
	v_add3_u32 v158, s5, v183, v181
	v_add_f32_e32 v191, v191, v86
	v_add_f32_e32 v192, v192, v87
	v_cvt_pk_bf16_f32 v196, v86, v87
	v_add_f32_e32 v191, v191, v88
	v_add_f32_e32 v192, v192, v89
	v_cvt_pk_bf16_f32 v197, v88, v89
	v_mfma_f32_32x32x16_bf16 v[98:113], v[218:221], v[122:125], v[98:113]
	s_waitcnt vmcnt(3)
	ds_write_b128 v158, v[130:133] offset:34816
	v_sub_f32_e32 v90, v90, v239
	v_sub_f32_e32 v91, v91, v239
	v_sub_f32_e32 v92, v92, v239
	v_sub_f32_e32 v93, v93, v239
	v_exp_f32_e32 v90, v90
	s_waitcnt lgkmcnt(4)
	v_mfma_f32_32x32x16_bf16 v[48:63], v[226:229], v[206:209], v[48:63]
	ds_read_b128 v[226:229], v235 offset:18432
	s_waitcnt vmcnt(2)
	ds_write_b128 v158, v[134:137] offset:44032
	v_exp_f32_e32 v91, v91
	v_exp_f32_e32 v92, v92
	v_exp_f32_e32 v93, v93
	s_waitcnt lgkmcnt(5)
	v_mfma_f32_32x32x16_bf16 v[32:47], v[230:233], v[206:209], v[32:47]
	ds_read_b128 v[230:233], v235 offset:23040
	s_waitcnt vmcnt(1)
	ds_write_b128 v158, v[138:141] offset:53248
	v_add_f32_e32 v191, v191, v90
	v_add_f32_e32 v192, v192, v91
	v_cvt_pk_bf16_f32 v198, v90, v91
	v_add_f32_e32 v191, v191, v92
	v_add_f32_e32 v192, v192, v93
	v_cvt_pk_bf16_f32 v199, v92, v93
	v_mfma_f32_32x32x16_bf16 v[98:113], v[222:225], v[126:129], v[98:113]
	s_waitcnt vmcnt(0)
	ds_write_b128 v158, v[142:145] offset:62464
	v_sub_f32_e32 v94, v94, v239
	v_sub_f32_e32 v95, v95, v239
	v_sub_f32_e32 v96, v96, v239
	v_sub_f32_e32 v97, v97, v239
	v_exp_f32_e32 v94, v94
	s_waitcnt lgkmcnt(7)
	v_mfma_f32_32x32x16_bf16 v[16:31], v[174:177], v[206:209], v[16:31]
	ds_read_b128 v[174:177], v235 offset:27648
	v_exp_f32_e32 v95, v95
	v_exp_f32_e32 v96, v96
	v_exp_f32_e32 v97, v97
	s_waitcnt lgkmcnt(7)
	v_mfma_f32_32x32x16_bf16 v[0:15], v[246:249], v[206:209], v[0:15]
	ds_read_b128 v[246:249], v235 offset:32256
	v_add_f32_e32 v191, v191, v94
	v_add_f32_e32 v192, v192, v95
	v_cvt_pk_bf16_f32 v200, v94, v95
	v_add_f32_e32 v191, v191, v96
	v_add_f32_e32 v192, v192, v97
	v_cvt_pk_bf16_f32 v201, v96, v97
	s_waitcnt lgkmcnt(0)
	s_barrier
	s_add_i32 s16, s4, 1
	s_cmp_lg_u32 s16, s9
	s_cbranch_scc1 .Lda_nocflip
	v_xor_b32_e32 v66, 0x80000000, v66
	v_xor_b32_e32 v67, 0x80000000, v67
	v_xor_b32_e32 v68, 0x80000000, v68
	v_xor_b32_e32 v69, 0x80000000, v69
	v_xor_b32_e32 v70, 0x80000000, v70
	v_xor_b32_e32 v71, 0x80000000, v71
	v_xor_b32_e32 v72, 0x80000000, v72
	v_xor_b32_e32 v73, 0x80000000, v73
	v_xor_b32_e32 v74, 0x80000000, v74
	v_xor_b32_e32 v75, 0x80000000, v75
	v_xor_b32_e32 v76, 0x80000000, v76
	v_xor_b32_e32 v77, 0x80000000, v77
	v_xor_b32_e32 v78, 0x80000000, v78
	v_xor_b32_e32 v79, 0x80000000, v79
	v_xor_b32_e32 v80, 0x80000000, v80
	v_xor_b32_e32 v81, 0x80000000, v81
; __device__ void da_unit(char* lds, const Params& p, int layer, int unit) {
;     ...
;         if (it + 1 < NT) {
; #pragma unroll
;             for (int j = 0; j < 4; ++j) rk[j] = *(const u32x4*)(Kg + (size_t)tn * 16384 + j * 4096);
;         }
.Lda_nocflip:
	ds_read_b128 v[210:213], v236 offset:0
	ds_read_b128 v[214:217], v236 offset:32
	ds_read_b128 v[218:221], v236 offset:64
	ds_read_b128 v[222:225], v236 offset:96
	v_mfma_f32_32x32x16_bf16 v[48:63], v[226:229], v[194:197], v[48:63]
	ds_read_b128 v[226:229], v235 offset:18464
	s_lshl_b32 s18, s3, 15
	s_mov_b32 s19, 0
	v_lshl_add_u64 v[156:157], v[148:149], 0, s[18:19]
	global_load_dwordx4 v[130:133], v[156:157], off
	v_sub_f32_e32 v98, v98, v241
	v_sub_f32_e32 v99, v99, v241
	v_sub_f32_e32 v100, v100, v241
	v_sub_f32_e32 v101, v101, v241
	v_exp_f32_e32 v98, v98
	v_mfma_f32_32x32x16_bf16 v[32:47], v[230:233], v[194:197], v[32:47]
	ds_read_b128 v[230:233], v235 offset:23072
	s_add_u32 s18, s18, 0x2000
	v_lshl_add_u64 v[156:157], v[148:149], 0, s[18:19]
	global_load_dwordx4 v[134:137], v[156:157], off
	v_exp_f32_e32 v99, v99
	v_exp_f32_e32 v100, v100
	v_exp_f32_e32 v101, v101
	s_waitcnt lgkmcnt(5)
	v_mfma_f32_32x32x16_bf16 v[82:97], v[210:213], v[114:117], v[66:81]
	ds_read_b128 v[210:213], v236 offset:8704
	s_add_u32 s18, s18, 0x2000
	v_lshl_add_u64 v[156:157], v[148:149], 0, s[18:19]
	global_load_dwordx4 v[138:141], v[156:157], off
	v_add_f32_e32 v191, v191, v98
	v_add_f32_e32 v192, v192, v99
	v_cvt_pk_bf16_f32 v202, v98, v99
	v_add_f32_e32 v191, v191, v100
	v_add_f32_e32 v192, v192, v101
	v_cvt_pk_bf16_f32 v203, v100, v101
	v_mfma_f32_32x32x16_bf16 v[16:31], v[174:177], v[194:197], v[16:31]
	ds_read_b128 v[174:177], v235 offset:27680
	s_add_u32 s18, s18, 0x2000
	v_lshl_add_u64 v[156:157], v[148:149], 0, s[18:19]
	global_load_dwordx4 v[142:145], v[156:157], off
	v_sub_f32_e32 v102, v102, v241
	v_sub_f32_e32 v103, v103, v241
	v_sub_f32_e32 v104, v104, v241
	v_sub_f32_e32 v105, v105, v241
	v_exp_f32_e32 v102, v102
	v_mfma_f32_32x32x16_bf16 v[0:15], v[246:249], v[194:197], v[0:15]
	ds_read_b128 v[246:249], v235 offset:32288
	v_exp_f32_e32 v103, v103
	v_exp_f32_e32 v104, v104
	v_exp_f32_e32 v105, v105
	s_waitcnt lgkmcnt(7)
	v_mfma_f32_32x32x16_bf16 v[82:97], v[214:217], v[118:121], v[82:97]
	ds_read_b128 v[214:217], v236 offset:8736
	v_add_f32_e32 v191, v191, v102
	v_add_f32_e32 v192, v192, v103
	v_cvt_pk_bf16_f32 v204, v102, v103
	v_add_f32_e32 v191, v191, v104
	v_add_f32_e32 v192, v192, v105
	v_cvt_pk_bf16_f32 v205, v104, v105
	s_waitcnt lgkmcnt(5)
	v_mfma_f32_32x32x16_bf16 v[48:63], v[226:229], v[198:201], v[48:63]
	ds_read_b128 v[226:229], v235 offset:18496
	v_sub_f32_e32 v106, v106, v241
	v_sub_f32_e32 v107, v107, v241
	v_sub_f32_e32 v108, v108, v241
	v_sub_f32_e32 v109, v109, v241
	v_exp_f32_e32 v106, v106
	s_waitcnt lgkmcnt(5)
	v_mfma_f32_32x32x16_bf16 v[32:47], v[230:233], v[198:201], v[32:47]
	ds_read_b128 v[230:233], v235 offset:23104
	v_exp_f32_e32 v107, v107
	v_exp_f32_e32 v108, v108
	v_exp_f32_e32 v109, v109
	v_mfma_f32_32x32x16_bf16 v[82:97], v[218:221], v[122:125], v[82:97]
	ds_read_b128 v[218:221], v236 offset:8768
	v_add_f32_e32 v191, v191, v106
	v_add_f32_e32 v192, v192, v107
	v_cvt_pk_bf16_f32 v206, v106, v107
	v_add_f32_e32 v191, v191, v108
	v_add_f32_e32 v192, v192, v109
	v_cvt_pk_bf16_f32 v207, v108, v109
	s_waitcnt lgkmcnt(5)
	v_mfma_f32_32x32x16_bf16 v[16:31], v[174:177], v[198:201], v[16:31]
	ds_read_b128 v[174:177], v235 offset:27712
	v_sub_f32_e32 v110, v110, v241
	v_sub_f32_e32 v111, v111, v241
	v_sub_f32_e32 v112, v112, v241
	v_sub_f32_e32 v113, v113, v241
	v_exp_f32_e32 v110, v110
	s_waitcnt lgkmcnt(5)
	v_mfma_f32_32x32x16_bf16 v[0:15], v[246:249], v[198:201], v[0:15]
	ds_read_b128 v[246:249], v235 offset:32320
	v_exp_f32_e32 v111, v111
	v_exp_f32_e32 v112, v112
	v_exp_f32_e32 v113, v113
	v_mfma_f32_32x32x16_bf16 v[82:97], v[222:225], v[126:129], v[82:97]
	ds_read_b128 v[222:225], v236 offset:8800
	v_add_f32_e32 v191, v191, v110
	v_add_f32_e32 v192, v192, v111
	v_cvt_pk_bf16_f32 v208, v110, v111
	v_add_f32_e32 v191, v191, v112
	v_add_f32_e32 v192, v192, v113
	v_cvt_pk_bf16_f32 v209, v112, v113
	s_add_i32 s4, s4, 1
	s_cmp_lt_u32 s4, 16
	s_waitcnt lgkmcnt(0)
	s_cbranch_scc1 .Lda_top
	v_mfma_f32_32x32x16_bf16 v[48:63], v[226:229], v[202:205], v[48:63]
	ds_read_b128 v[226:229], v235 offset:18528
	v_mfma_f32_32x32x16_bf16 v[32:47], v[230:233], v[202:205], v[32:47]
	ds_read_b128 v[230:233], v235 offset:23136
	v_mfma_f32_32x32x16_bf16 v[16:31], v[174:177], v[202:205], v[16:31]
	ds_read_b128 v[174:177], v235 offset:27744
	v_mfma_f32_32x32x16_bf16 v[0:15], v[246:249], v[202:205], v[0:15]
	ds_read_b128 v[246:249], v235 offset:32352
	s_waitcnt lgkmcnt(3)
	v_mfma_f32_32x32x16_bf16 v[48:63], v[226:229], v[206:209], v[48:63]
	s_waitcnt lgkmcnt(2)
	v_mfma_f32_32x32x16_bf16 v[32:47], v[230:233], v[206:209], v[32:47]
	s_waitcnt lgkmcnt(1)
	v_mfma_f32_32x32x16_bf16 v[16:31], v[174:177], v[206:209], v[16:31]
	s_waitcnt lgkmcnt(0)
	v_mfma_f32_32x32x16_bf16 v[0:15], v[246:249], v[206:209], v[0:15]
	v_add_f32_e32 v191, v191, v192
	s_waitcnt vmcnt(0)
	s_nop 7
	s_nop 3
	v_add_f32_e32 v193, v193, v191
